# attention work queue: next unit id fetched at the start of the unit epilogue (latency hidden behind the gate/store tail), LDS hand-over with one barrier
# speedup vs baseline: 1.0008x; 1.0008x over previous
.LBB0_790:
	s_waitcnt vmcnt(0)
	s_and_saveexec_b64 s[8:9], vcc
	v_mov_b32_e32 v251, 0x9200
	ds_write_b32 v251, v250
	s_or_b64 exec, exec, s[8:9]
	s_waitcnt lgkmcnt(0)
	s_barrier
	v_mov_b32_e32 v0, 0x9200
	ds_read_b32 v0, v0
	s_movk_i32 s0, 0x480
	s_mov_b64 s[8:9], -1
	s_waitcnt lgkmcnt(0)
	v_cmp_gt_i32_e64 s[6:7], s0, v0
	s_and_saveexec_b64 s[68:69], s[6:7]
	s_cbranch_execz .LBB0_789
	v_ashrrev_i32_e32 v1, 31, v0
	v_lshrrev_b32_e32 v1, 25, v1
	v_add_u32_e32 v1, v0, v1
	v_ashrrev_i32_e32 v8, 7, v1
	v_and_b32_e32 v1, 0xffffff80, v1
	v_sub_u32_e32 v0, v0, v1
	v_mov_b32_e32 v1, 11
	v_lshrrev_b16_sdwa v1, v1, sext(v0) dst_sel:DWORD dst_unused:UNUSED_PAD src0_sel:DWORD src1_sel:BYTE_0
	v_and_b32_e32 v1, 15, v1
	v_add_u16_e32 v1, v0, v1
	v_sub_u32_e32 v9, 8, v8
	v_ashrrev_i16_sdwa v2, v198, sext(v1) dst_sel:DWORD dst_unused:UNUSED_PAD src0_sel:DWORD src1_sel:BYTE_0
	s_movk_i32 s0, 0x810
	v_and_b32_e32 v1, 0xf0, v1
	v_mul_hi_i32_i24_sdwa v135, sext(v2), s0 dst_sel:DWORD dst_unused:UNUSED_PAD src0_sel:WORD_0 src1_sel:DWORD
	v_mul_i32_i24_sdwa v134, sext(v2), s0 dst_sel:DWORD dst_unused:UNUSED_PAD src0_sel:WORD_0 src1_sel:DWORD
	v_mul_hi_i32_i24_e32 v3, 0x2040, v0
	v_mul_i32_i24_e32 v2, 0x2040, v0
	v_lshlrev_b32_e32 v10, 8, v9
	v_sub_u16_e32 v4, v0, v1
	v_lshl_add_u64 v[140:141], s[62:63], 0, v[2:3]
	v_add_u32_e32 v164, v10, v156
	v_mov_b32_e32 v2, 6
	v_lshlrev_b32_sdwa v138, v2, sext(v4) dst_sel:DWORD dst_unused:UNUSED_PAD src0_sel:DWORD src1_sel:BYTE_0
	v_max_i32_e32 v6, 0xf0, v164
	v_ashrrev_i32_e32 v139, 31, v138
	v_add_u32_e32 v172, 0xffffff10, v6
	v_lshlrev_b64 v[2:3], 1, v[138:139]
	v_lshl_add_u64 v[6:7], v[134:135], 0, v[172:173]
	v_lshl_add_u64 v[4:5], v[120:121], 0, v[2:3]
	v_lshlrev_b64 v[6:7], 12, v[6:7]
	v_lshl_add_u64 v[6:7], v[4:5], 0, v[6:7]
	v_or_b32_e32 v139, 16, v164
	global_load_dwordx4 v[20:23], v[6:7], off
	global_load_dwordx4 v[24:27], v[6:7], off offset:64
	v_max_i32_e32 v6, 0xf0, v139
	v_add_u32_e32 v172, 0xffffff10, v6
	v_lshl_add_u64 v[6:7], v[134:135], 0, v[172:173]
	v_lshlrev_b64 v[6:7], 12, v[6:7]
	v_ashrrev_i32_e32 v1, 31, v0
	v_lshl_add_u64 v[4:5], v[4:5], 0, v[6:7]
	global_load_dwordx4 v[28:31], v[4:5], off
	global_load_dwordx4 v[32:35], v[4:5], off offset:64
	v_lshl_add_u64 v[4:5], v[134:135], 0, v[124:125]
	v_lshlrev_b64 v[0:1], 6, v[0:1]
	v_lshlrev_b64 v[4:5], 11, v[4:5]
	v_lshl_add_u64 v[0:1], v[0:1], 0, v[122:123]
	v_mov_b64_e32 v[6:7], s[88:89]
	v_lshl_add_u64 v[4:5], s[70:71], 0, v[4:5]
	v_mad_u64_u32 v[144:145], s[6:7], v0, s52, v[6:7]
	v_lshl_add_u64 v[4:5], v[4:5], 0, v[2:3]
	v_lshlrev_b32_e32 v142, 1, v126
	v_mov_b32_e32 v143, v173
	v_mad_i32_i24 v145, v1, s52, v145
	v_mov_b32_e32 v131, v173
	v_lshlrev_b32_e32 v165, 2, v9
	v_lshl_add_u64 v[4:5], v[4:5], 0, v[142:143]
	v_lshl_add_u64 v[0:1], v[144:145], 0, v[130:131]
	v_mov_b32_e32 v133, v173
	v_or_b32_e32 v166, 3, v165
	global_load_dwordx4 v[36:39], v[4:5], off
	global_load_dwordx4 v[40:43], v[0:1], off offset:-96
	v_lshl_add_u64 v[0:1], v[140:141], 0, v[132:133]
	global_load_dword v131, v[0:1], off offset:-192
	v_min_u32_e32 v0, 4, v166
	v_lshl_add_u32 v6, v0, 6, v201
	v_add_u32_e32 v0, v6, v122
	v_max_i32_e32 v172, 0, v0
	v_lshl_add_u64 v[0:1], v[134:135], 0, v[172:173]
	v_lshlrev_b64 v[0:1], 11, v[0:1]
	v_lshl_add_u64 v[0:1], s[70:71], 0, v[0:1]
	v_add_u32_e32 v4, v6, v126
	v_lshl_add_u64 v[0:1], v[0:1], 0, v[2:3]
	v_max_i32_e32 v4, 0, v4
	v_lshl_add_u64 v[0:1], v[0:1], 0, v[142:143]
	v_lshlrev_b32_e32 v172, 1, v4
	v_lshl_add_u64 v[4:5], v[144:145], 0, v[172:173]
	global_load_dwordx4 v[44:47], v[0:1], off
	global_load_dwordx4 v[48:51], v[4:5], off
	v_add_u32_e32 v0, v6, v154
	v_max_i32_e32 v0, 0, v0
	v_lshlrev_b32_e32 v172, 2, v0
	v_lshl_add_u64 v[0:1], v[140:141], 0, v[172:173]
	global_load_dword v167, v[0:1], off
	v_min_u32_e32 v0, 5, v166
	v_lshl_add_u32 v6, v0, 6, v201
	v_add_u32_e32 v0, v6, v122
	v_max_i32_e32 v172, 0, v0
	v_lshl_add_u64 v[0:1], v[134:135], 0, v[172:173]
	v_lshlrev_b64 v[0:1], 11, v[0:1]
	v_lshl_add_u64 v[0:1], s[70:71], 0, v[0:1]
	v_add_u32_e32 v4, v6, v126
	v_lshl_add_u64 v[0:1], v[0:1], 0, v[2:3]
	v_max_i32_e32 v4, 0, v4
	v_lshl_add_u64 v[0:1], v[0:1], 0, v[142:143]
	v_lshlrev_b32_e32 v172, 1, v4
	v_lshl_add_u64 v[4:5], v[144:145], 0, v[172:173]
	global_load_dwordx4 v[52:55], v[0:1], off
	global_load_dwordx4 v[56:59], v[4:5], off
	v_add_u32_e32 v0, v6, v154
	v_max_i32_e32 v0, 0, v0
	v_lshlrev_b32_e32 v172, 2, v0
	v_lshl_add_u64 v[0:1], v[140:141], 0, v[172:173]
	global_load_dword v169, v[0:1], off
	v_sub_u32_e32 v0, 0, v8
	v_or_b32_e32 v1, v10, v155
	v_lshl_add_u64 v[146:147], v[128:129], 0, v[2:3]
	v_lshlrev_b32_e32 v0, 8, v0
	v_mov_b32_e32 v2, v173
	v_mov_b32_e32 v3, v173
	v_add_u32_e32 v133, s85, v1
	v_sub_u32_e32 v168, 0, v0
	v_mov_b32_e32 v172, v173
	v_mov_b32_e32 v0, v173
	v_mov_b32_e32 v1, v173
	v_mov_b64_e32 v[6:7], v[2:3]
	v_mov_b64_e32 v[10:11], v[2:3]
	v_mov_b64_e32 v[14:15], v[2:3]
	v_mov_b64_e32 v[18:19], v[2:3]
	v_mov_b64_e32 v[62:63], v[2:3]
	v_mov_b64_e32 v[66:67], v[2:3]
	v_mov_b64_e32 v[70:71], v[2:3]
	s_mov_b32 s60, s87
	s_mov_b32 s84, 0
	v_or_b32_e32 v143, 16, v133
	v_mov_b32_e32 v148, 0xff800000
	s_mov_b64 s[34:35], 0
	v_mov_b32_e32 v170, 0
	s_mov_b32 s87, 0
	v_mov_b64_e32 v[4:5], v[0:1]
	v_mov_b64_e32 v[8:9], v[0:1]
	v_mov_b64_e32 v[12:13], v[0:1]
	v_mov_b64_e32 v[16:17], v[0:1]
	v_mov_b64_e32 v[60:61], v[0:1]
	v_mov_b64_e32 v[64:65], v[0:1]
	v_mov_b64_e32 v[68:69], v[0:1]
	v_mov_b64_e32 v[136:137], v[172:173]
	v_mov_b32_e32 v149, 0xff800000
	s_branch .LBB0_798

.LBB0_827:
	s_or_b64 exec, exec, s[34:35]
	s_mov_b64 exec, vcc
	s_cbranch_execz .Lattn_q_skip1
	v_readlane_b32 s100, v253, 38
	v_readlane_b32 s101, v253, 39
	v_mov_b32_e32 v251, 1
	s_nop 3
	global_atomic_add v250, v173, v251, s[100:101] offset:64 sc0
.Lattn_q_skip1:
	s_mov_b64 exec, -1
	ds_bpermute_b32 v20, v160, v136
	s_movk_i32 s0, 0xef
	v_cmp_lt_i32_e64 s[6:7], s0, v164
	s_waitcnt lgkmcnt(0)
	v_add_f32_e32 v22, v136, v20
	ds_bpermute_b32 v23, v161, v22
	v_or_b32_e32 v20, v138, v158
	v_ashrrev_i32_e32 v21, 31, v20
	s_and_saveexec_b64 s[8:9], s[6:7]
	s_cbranch_execz .LBB0_829
	v_add_u32_e32 v172, 0xffffff10, v164
	v_lshl_add_u64 v[24:25], v[134:135], 0, v[172:173]
	v_lshlrev_b64 v[26:27], 12, v[24:25]
	v_lshl_add_u64 v[26:27], s[54:55], 0, v[26:27]
	v_lshlrev_b64 v[28:29], 1, v[20:21]
	v_lshl_add_u64 v[26:27], v[26:27], 0, v[28:29]
	global_load_dwordx2 v[30:31], v[26:27], off offset:2048
	v_lshlrev_b64 v[24:25], 11, v[24:25]
	v_lshl_add_u64 v[24:25], s[44:45], 0, v[24:25]
	v_lshl_add_u64 v[24:25], v[24:25], 0, v[28:29]
	global_load_dwordx2 v[28:29], v[26:27], off offset:2080
	s_waitcnt lgkmcnt(0)
	v_add_f32_e32 v22, v22, v23
	v_rcp_f32_e32 v22, v22
	v_mov_b32_e32 v34, v68
	v_mov_b32_e32 v35, v70
	v_mov_b32_e32 v70, v69
	s_waitcnt vmcnt(1)
	v_lshlrev_b32_e32 v23, 16, v30
	v_mul_f32_e32 v23, 0xbfb8aa3b, v23
	v_exp_f32_e32 v23, v23
	s_nop 0
	v_add_f32_e32 v23, 1.0, v23
	v_rcp_f32_e32 v32, v23
	v_and_b32_e32 v23, 0xffff0000, v30
	v_mul_f32_e32 v23, 0xbfb8aa3b, v23
	v_exp_f32_e32 v23, v23
	s_nop 0
	v_add_f32_e32 v23, 1.0, v23
	v_rcp_f32_e32 v30, v23
	v_lshlrev_b32_e32 v23, 16, v31
	v_mul_f32_e32 v23, 0xbfb8aa3b, v23
	v_exp_f32_e32 v23, v23
	s_nop 0
	v_add_f32_e32 v23, 1.0, v23
	v_rcp_f32_e32 v33, v23
	v_and_b32_e32 v23, 0xffff0000, v31
	v_mul_f32_e32 v23, 0xbfb8aa3b, v23
	v_exp_f32_e32 v23, v23
	s_nop 0
	v_add_f32_e32 v23, 1.0, v23
	v_rcp_f32_e32 v31, v23
	v_pk_mul_f32 v[34:35], v[34:35], v[22:23] op_sel_hi:[1,0]
	s_nop 0
	v_pk_mul_f32 v[32:33], v[34:35], v[32:33]
	v_pk_mul_f32 v[34:35], v[70:71], v[22:23] op_sel_hi:[1,0]
	v_and_b32_sdwa v23, v33, v196 dst_sel:DWORD dst_unused:UNUSED_PAD src0_sel:WORD_1 src1_sel:DWORD
	v_pk_mul_f32 v[30:31], v[34:35], v[30:31]
	v_add3_u32 v23, v33, v23, s96
	v_and_b32_sdwa v33, v31, v196 dst_sel:DWORD dst_unused:UNUSED_PAD src0_sel:WORD_1 src1_sel:DWORD
	v_add3_u32 v31, v31, v33, s96
	v_and_b32_e32 v31, 0xffff0000, v31
	v_or_b32_sdwa v31, v31, v23 dst_sel:DWORD dst_unused:UNUSED_PAD src0_sel:DWORD src1_sel:WORD_1
	s_waitcnt vmcnt(0)
	v_lshlrev_b32_e32 v23, 16, v28
	v_mul_f32_e32 v23, 0xbfb8aa3b, v23
	v_and_b32_sdwa v34, v32, v196 dst_sel:DWORD dst_unused:UNUSED_PAD src0_sel:WORD_1 src1_sel:DWORD
	v_exp_f32_e32 v23, v23
	v_add3_u32 v32, v32, v34, s96
	v_and_b32_sdwa v34, v30, v196 dst_sel:DWORD dst_unused:UNUSED_PAD src0_sel:WORD_1 src1_sel:DWORD
	v_add3_u32 v30, v30, v34, s96
	v_and_b32_e32 v30, 0xffff0000, v30
	v_or_b32_sdwa v30, v30, v32 dst_sel:DWORD dst_unused:UNUSED_PAD src0_sel:DWORD src1_sel:WORD_1
	v_add_f32_e32 v23, 1.0, v23
	global_store_dwordx2 v[24:25], v[30:31], off
	v_rcp_f32_e32 v30, v23
	v_and_b32_e32 v23, 0xffff0000, v28
	v_mul_f32_e32 v23, 0xbfb8aa3b, v23
	v_exp_f32_e32 v23, v23
	v_mov_b32_e32 v32, v64
	v_mov_b32_e32 v33, v66
	v_mov_b32_e32 v66, v65
	v_add_f32_e32 v23, 1.0, v23
	v_rcp_f32_e32 v28, v23
	v_lshlrev_b32_e32 v23, 16, v29
	v_mul_f32_e32 v23, 0xbfb8aa3b, v23
	v_exp_f32_e32 v23, v23
	s_nop 0
	v_add_f32_e32 v23, 1.0, v23
	v_rcp_f32_e32 v31, v23
	v_and_b32_e32 v23, 0xffff0000, v29
	v_mul_f32_e32 v23, 0xbfb8aa3b, v23
	v_exp_f32_e32 v23, v23
	s_nop 0
	v_add_f32_e32 v23, 1.0, v23
	v_rcp_f32_e32 v29, v23
	v_pk_mul_f32 v[32:33], v[32:33], v[22:23] op_sel_hi:[1,0]
	s_nop 0
	v_pk_mul_f32 v[30:31], v[32:33], v[30:31]
	v_pk_mul_f32 v[32:33], v[66:67], v[22:23] op_sel_hi:[1,0]
	v_and_b32_sdwa v23, v31, v196 dst_sel:DWORD dst_unused:UNUSED_PAD src0_sel:WORD_1 src1_sel:DWORD
	v_pk_mul_f32 v[28:29], v[32:33], v[28:29]
	v_and_b32_sdwa v32, v30, v196 dst_sel:DWORD dst_unused:UNUSED_PAD src0_sel:WORD_1 src1_sel:DWORD
	v_add3_u32 v30, v30, v32, s96
	v_add3_u32 v23, v31, v23, s96
	v_and_b32_sdwa v31, v29, v196 dst_sel:DWORD dst_unused:UNUSED_PAD src0_sel:WORD_1 src1_sel:DWORD
	v_and_b32_sdwa v32, v28, v196 dst_sel:DWORD dst_unused:UNUSED_PAD src0_sel:WORD_1 src1_sel:DWORD
	v_add3_u32 v29, v29, v31, s96
	v_add3_u32 v28, v28, v32, s96
	v_and_b32_e32 v29, 0xffff0000, v29
	v_and_b32_e32 v28, 0xffff0000, v28
	v_or_b32_sdwa v29, v29, v23 dst_sel:DWORD dst_unused:UNUSED_PAD src0_sel:DWORD src1_sel:WORD_1
	v_or_b32_sdwa v28, v28, v30 dst_sel:DWORD dst_unused:UNUSED_PAD src0_sel:DWORD src1_sel:WORD_1
	global_store_dwordx2 v[24:25], v[28:29], off offset:32
	global_load_dwordx2 v[28:29], v[26:27], off offset:2112
	v_mov_b32_e32 v32, v60
	global_load_dwordx2 v[26:27], v[26:27], off offset:2144
	v_mov_b32_e32 v33, v62
	v_mov_b32_e32 v62, v61
	s_waitcnt vmcnt(1)
	v_lshlrev_b32_e32 v23, 16, v28
	v_mul_f32_e32 v23, 0xbfb8aa3b, v23
	v_exp_f32_e32 v23, v23
	s_nop 0
	v_add_f32_e32 v23, 1.0, v23
	v_rcp_f32_e32 v30, v23
	v_and_b32_e32 v23, 0xffff0000, v28
	v_mul_f32_e32 v23, 0xbfb8aa3b, v23
	v_exp_f32_e32 v23, v23
	s_nop 0
	v_add_f32_e32 v23, 1.0, v23
	v_rcp_f32_e32 v28, v23
	v_lshlrev_b32_e32 v23, 16, v29
	v_mul_f32_e32 v23, 0xbfb8aa3b, v23
	v_exp_f32_e32 v23, v23
	s_nop 0
	v_add_f32_e32 v23, 1.0, v23
	v_rcp_f32_e32 v31, v23
	v_and_b32_e32 v23, 0xffff0000, v29
	v_mul_f32_e32 v23, 0xbfb8aa3b, v23
	v_exp_f32_e32 v23, v23
	s_nop 0
	v_add_f32_e32 v23, 1.0, v23
	v_rcp_f32_e32 v29, v23
	v_pk_mul_f32 v[32:33], v[32:33], v[22:23] op_sel_hi:[1,0]
	s_nop 0
	v_pk_mul_f32 v[30:31], v[32:33], v[30:31]
	v_pk_mul_f32 v[32:33], v[62:63], v[22:23] op_sel_hi:[1,0]
	v_and_b32_sdwa v23, v31, v196 dst_sel:DWORD dst_unused:UNUSED_PAD src0_sel:WORD_1 src1_sel:DWORD
	v_pk_mul_f32 v[28:29], v[32:33], v[28:29]
	v_add3_u32 v23, v31, v23, s96
	v_and_b32_sdwa v31, v29, v196 dst_sel:DWORD dst_unused:UNUSED_PAD src0_sel:WORD_1 src1_sel:DWORD
	v_add3_u32 v29, v29, v31, s96
	v_and_b32_e32 v29, 0xffff0000, v29
	v_or_b32_sdwa v29, v29, v23 dst_sel:DWORD dst_unused:UNUSED_PAD src0_sel:DWORD src1_sel:WORD_1
	s_waitcnt vmcnt(0)
	v_lshlrev_b32_e32 v23, 16, v26
	v_mul_f32_e32 v23, 0xbfb8aa3b, v23
	v_and_b32_sdwa v32, v30, v196 dst_sel:DWORD dst_unused:UNUSED_PAD src0_sel:WORD_1 src1_sel:DWORD
	v_exp_f32_e32 v23, v23
	v_add3_u32 v30, v30, v32, s96
	v_and_b32_sdwa v32, v28, v196 dst_sel:DWORD dst_unused:UNUSED_PAD src0_sel:WORD_1 src1_sel:DWORD
	v_add3_u32 v28, v28, v32, s96
	v_and_b32_e32 v28, 0xffff0000, v28
	v_or_b32_sdwa v28, v28, v30 dst_sel:DWORD dst_unused:UNUSED_PAD src0_sel:DWORD src1_sel:WORD_1
	v_add_f32_e32 v23, 1.0, v23
	global_store_dwordx2 v[24:25], v[28:29], off offset:64
	v_rcp_f32_e32 v28, v23
	v_and_b32_e32 v23, 0xffff0000, v26
	v_mul_f32_e32 v23, 0xbfb8aa3b, v23
	v_exp_f32_e32 v23, v23
	v_mov_b32_e32 v31, v18
	v_mov_b32_e32 v18, v17
	v_mov_b32_e32 v30, v16
	v_add_f32_e32 v23, 1.0, v23
	v_rcp_f32_e32 v26, v23
	v_lshlrev_b32_e32 v23, 16, v27
	v_mul_f32_e32 v23, 0xbfb8aa3b, v23
	v_exp_f32_e32 v23, v23
	s_nop 0
	v_add_f32_e32 v23, 1.0, v23
	v_rcp_f32_e32 v29, v23
	v_and_b32_e32 v23, 0xffff0000, v27
	v_mul_f32_e32 v23, 0xbfb8aa3b, v23
	v_exp_f32_e32 v23, v23
	s_nop 0
	v_add_f32_e32 v23, 1.0, v23
	v_rcp_f32_e32 v27, v23
	v_pk_mul_f32 v[16:17], v[18:19], v[22:23] op_sel_hi:[1,0]
	v_pk_mul_f32 v[30:31], v[30:31], v[22:23] op_sel_hi:[1,0]
	v_pk_mul_f32 v[16:17], v[16:17], v[26:27]
	v_pk_mul_f32 v[28:29], v[30:31], v[28:29]
	v_and_b32_sdwa v22, v17, v196 dst_sel:DWORD dst_unused:UNUSED_PAD src0_sel:WORD_1 src1_sel:DWORD
	v_and_b32_sdwa v23, v16, v196 dst_sel:DWORD dst_unused:UNUSED_PAD src0_sel:WORD_1 src1_sel:DWORD
	v_and_b32_sdwa v18, v29, v196 dst_sel:DWORD dst_unused:UNUSED_PAD src0_sel:WORD_1 src1_sel:DWORD
	v_and_b32_sdwa v19, v28, v196 dst_sel:DWORD dst_unused:UNUSED_PAD src0_sel:WORD_1 src1_sel:DWORD
	v_add3_u32 v17, v17, v22, s96
	v_add3_u32 v16, v16, v23, s96
	v_add3_u32 v19, v28, v19, s96
	v_add3_u32 v18, v29, v18, s96
	v_and_b32_e32 v17, 0xffff0000, v17
	v_and_b32_e32 v16, 0xffff0000, v16
	v_or_b32_sdwa v17, v17, v18 dst_sel:DWORD dst_unused:UNUSED_PAD src0_sel:DWORD src1_sel:WORD_1
	v_or_b32_sdwa v16, v16, v19 dst_sel:DWORD dst_unused:UNUSED_PAD src0_sel:DWORD src1_sel:WORD_1
	global_store_dwordx2 v[24:25], v[16:17], off offset:96
